# b12 + CMP2 dot product unrolled with LDS reads two groups ahead
# speedup vs baseline: 1.0074x; 1.0074x over previous
.LBB0_1202:
	v_add_u32_e32 v15, 0x10000, v14
	ds_read2st64_b32 v[24:25], v13 offset0:0 offset1:1
	ds_read2st64_b32 v[26:27], v13 offset0:2 offset1:3
	ds_read2st64_b32 v[28:29], v13 offset0:4 offset1:5
	ds_read2st64_b32 v[30:31], v13 offset0:6 offset1:7
	ds_read_b128 v[16:19], v15
	ds_read_b128 v[20:23], v15 offset:16
	ds_read2st64_b32 v[44:45], v13 offset0:8 offset1:9
	ds_read2st64_b32 v[46:47], v13 offset0:10 offset1:11
	ds_read2st64_b32 v[48:49], v13 offset0:12 offset1:13
	ds_read2st64_b32 v[50:51], v13 offset0:14 offset1:15
	ds_read_b128 v[36:39], v15 offset:32
	ds_read_b128 v[40:43], v15 offset:48
	ds_read2st64_b32 v[60:61], v13 offset0:16 offset1:17
	ds_read2st64_b32 v[62:63], v13 offset0:18 offset1:19
	ds_read2st64_b32 v[64:65], v13 offset0:20 offset1:21
	ds_read2st64_b32 v[66:67], v13 offset0:22 offset1:23
	ds_read_b128 v[52:55], v15 offset:64
	ds_read_b128 v[56:59], v15 offset:80
	s_waitcnt lgkmcnt(12)
	v_fmac_f32_e32 v1, v16, v24
	v_fmac_f32_e32 v1, v17, v25
	v_fmac_f32_e32 v1, v18, v26
	v_fmac_f32_e32 v1, v19, v27
	v_fmac_f32_e32 v1, v20, v28
	v_fmac_f32_e32 v1, v21, v29
	v_fmac_f32_e32 v1, v22, v30
	v_fmac_f32_e32 v1, v23, v31
	ds_read2st64_b32 v[24:25], v13 offset0:24 offset1:25
	ds_read2st64_b32 v[26:27], v13 offset0:26 offset1:27
	ds_read2st64_b32 v[28:29], v13 offset0:28 offset1:29
	ds_read2st64_b32 v[30:31], v13 offset0:30 offset1:31
	ds_read_b128 v[16:19], v15 offset:96
	ds_read_b128 v[20:23], v15 offset:112
	s_waitcnt lgkmcnt(12)
	v_fmac_f32_e32 v1, v36, v44
	v_fmac_f32_e32 v1, v37, v45
	v_fmac_f32_e32 v1, v38, v46
	v_fmac_f32_e32 v1, v39, v47
	v_fmac_f32_e32 v1, v40, v48
	v_fmac_f32_e32 v1, v41, v49
	v_fmac_f32_e32 v1, v42, v50
	v_fmac_f32_e32 v1, v43, v51
	ds_read2st64_b32 v[44:45], v13 offset0:32 offset1:33
	ds_read2st64_b32 v[46:47], v13 offset0:34 offset1:35
	ds_read2st64_b32 v[48:49], v13 offset0:36 offset1:37
	ds_read2st64_b32 v[50:51], v13 offset0:38 offset1:39
	ds_read_b128 v[36:39], v15 offset:128
	ds_read_b128 v[40:43], v15 offset:144
	s_waitcnt lgkmcnt(12)
	v_fmac_f32_e32 v1, v52, v60
	v_fmac_f32_e32 v1, v53, v61
	v_fmac_f32_e32 v1, v54, v62
	v_fmac_f32_e32 v1, v55, v63
	v_fmac_f32_e32 v1, v56, v64
	v_fmac_f32_e32 v1, v57, v65
	v_fmac_f32_e32 v1, v58, v66
	v_fmac_f32_e32 v1, v59, v67
	ds_read2st64_b32 v[60:61], v13 offset0:40 offset1:41
	ds_read2st64_b32 v[62:63], v13 offset0:42 offset1:43
	ds_read2st64_b32 v[64:65], v13 offset0:44 offset1:45
	ds_read2st64_b32 v[66:67], v13 offset0:46 offset1:47
	ds_read_b128 v[52:55], v15 offset:160
	ds_read_b128 v[56:59], v15 offset:176
	s_waitcnt lgkmcnt(12)
	v_fmac_f32_e32 v1, v16, v24
	v_fmac_f32_e32 v1, v17, v25
	v_fmac_f32_e32 v1, v18, v26
	v_fmac_f32_e32 v1, v19, v27
	v_fmac_f32_e32 v1, v20, v28
	v_fmac_f32_e32 v1, v21, v29
	v_fmac_f32_e32 v1, v22, v30
	v_fmac_f32_e32 v1, v23, v31
	ds_read2st64_b32 v[24:25], v13 offset0:48 offset1:49
	ds_read2st64_b32 v[26:27], v13 offset0:50 offset1:51
	ds_read2st64_b32 v[28:29], v13 offset0:52 offset1:53
	ds_read2st64_b32 v[30:31], v13 offset0:54 offset1:55
	ds_read_b128 v[16:19], v15 offset:192
	ds_read_b128 v[20:23], v15 offset:208
	s_waitcnt lgkmcnt(12)
	v_fmac_f32_e32 v1, v36, v44
	v_fmac_f32_e32 v1, v37, v45
	v_fmac_f32_e32 v1, v38, v46
	v_fmac_f32_e32 v1, v39, v47
	v_fmac_f32_e32 v1, v40, v48
	v_fmac_f32_e32 v1, v41, v49
	v_fmac_f32_e32 v1, v42, v50
	v_fmac_f32_e32 v1, v43, v51
	ds_read2st64_b32 v[44:45], v13 offset0:56 offset1:57
	ds_read2st64_b32 v[46:47], v13 offset0:58 offset1:59
	ds_read2st64_b32 v[48:49], v13 offset0:60 offset1:61
	ds_read2st64_b32 v[50:51], v13 offset0:62 offset1:63
	ds_read_b128 v[36:39], v15 offset:224
	ds_read_b128 v[40:43], v15 offset:240
	s_waitcnt lgkmcnt(12)
	v_fmac_f32_e32 v1, v52, v60
	v_fmac_f32_e32 v1, v53, v61
	v_fmac_f32_e32 v1, v54, v62
	v_fmac_f32_e32 v1, v55, v63
	v_fmac_f32_e32 v1, v56, v64
	v_fmac_f32_e32 v1, v57, v65
	v_fmac_f32_e32 v1, v58, v66
	v_fmac_f32_e32 v1, v59, v67
	ds_read2st64_b32 v[60:61], v13 offset0:64 offset1:65
	ds_read2st64_b32 v[62:63], v13 offset0:66 offset1:67
	ds_read2st64_b32 v[64:65], v13 offset0:68 offset1:69
	ds_read2st64_b32 v[66:67], v13 offset0:70 offset1:71
	ds_read_b128 v[52:55], v15 offset:256
	ds_read_b128 v[56:59], v15 offset:272
	s_waitcnt lgkmcnt(12)
	v_fmac_f32_e32 v1, v16, v24
	v_fmac_f32_e32 v1, v17, v25
	v_fmac_f32_e32 v1, v18, v26
	v_fmac_f32_e32 v1, v19, v27
	v_fmac_f32_e32 v1, v20, v28
	v_fmac_f32_e32 v1, v21, v29
	v_fmac_f32_e32 v1, v22, v30
	v_fmac_f32_e32 v1, v23, v31
	ds_read2st64_b32 v[24:25], v13 offset0:72 offset1:73
	ds_read2st64_b32 v[26:27], v13 offset0:74 offset1:75
	ds_read2st64_b32 v[28:29], v13 offset0:76 offset1:77
	ds_read2st64_b32 v[30:31], v13 offset0:78 offset1:79
	ds_read_b128 v[16:19], v15 offset:288
	ds_read_b128 v[20:23], v15 offset:304
	s_waitcnt lgkmcnt(12)
	v_fmac_f32_e32 v1, v36, v44
	v_fmac_f32_e32 v1, v37, v45
	v_fmac_f32_e32 v1, v38, v46
	v_fmac_f32_e32 v1, v39, v47
	v_fmac_f32_e32 v1, v40, v48
	v_fmac_f32_e32 v1, v41, v49
	v_fmac_f32_e32 v1, v42, v50
	v_fmac_f32_e32 v1, v43, v51
	ds_read2st64_b32 v[44:45], v13 offset0:80 offset1:81
	ds_read2st64_b32 v[46:47], v13 offset0:82 offset1:83
	ds_read2st64_b32 v[48:49], v13 offset0:84 offset1:85
	ds_read2st64_b32 v[50:51], v13 offset0:86 offset1:87
	ds_read_b128 v[36:39], v15 offset:320
	ds_read_b128 v[40:43], v15 offset:336
	s_waitcnt lgkmcnt(12)
	v_fmac_f32_e32 v1, v52, v60
	v_fmac_f32_e32 v1, v53, v61
	v_fmac_f32_e32 v1, v54, v62
	v_fmac_f32_e32 v1, v55, v63
	v_fmac_f32_e32 v1, v56, v64
	v_fmac_f32_e32 v1, v57, v65
	v_fmac_f32_e32 v1, v58, v66
	v_fmac_f32_e32 v1, v59, v67
	ds_read2st64_b32 v[60:61], v13 offset0:88 offset1:89
	ds_read2st64_b32 v[62:63], v13 offset0:90 offset1:91
	ds_read2st64_b32 v[64:65], v13 offset0:92 offset1:93
	ds_read2st64_b32 v[66:67], v13 offset0:94 offset1:95
	ds_read_b128 v[52:55], v15 offset:352
	ds_read_b128 v[56:59], v15 offset:368
	s_waitcnt lgkmcnt(12)
	v_fmac_f32_e32 v1, v16, v24
	v_fmac_f32_e32 v1, v17, v25
	v_fmac_f32_e32 v1, v18, v26
	v_fmac_f32_e32 v1, v19, v27
	v_fmac_f32_e32 v1, v20, v28
	v_fmac_f32_e32 v1, v21, v29
	v_fmac_f32_e32 v1, v22, v30
	v_fmac_f32_e32 v1, v23, v31
	ds_read2st64_b32 v[24:25], v13 offset0:96 offset1:97
	ds_read2st64_b32 v[26:27], v13 offset0:98 offset1:99
	ds_read2st64_b32 v[28:29], v13 offset0:100 offset1:101
	ds_read2st64_b32 v[30:31], v13 offset0:102 offset1:103
	ds_read_b128 v[16:19], v15 offset:384
	ds_read_b128 v[20:23], v15 offset:400
	s_waitcnt lgkmcnt(12)
	v_fmac_f32_e32 v1, v36, v44
	v_fmac_f32_e32 v1, v37, v45
	v_fmac_f32_e32 v1, v38, v46
	v_fmac_f32_e32 v1, v39, v47
	v_fmac_f32_e32 v1, v40, v48
	v_fmac_f32_e32 v1, v41, v49
	v_fmac_f32_e32 v1, v42, v50
	v_fmac_f32_e32 v1, v43, v51
	ds_read2st64_b32 v[44:45], v13 offset0:104 offset1:105
	ds_read2st64_b32 v[46:47], v13 offset0:106 offset1:107
	ds_read2st64_b32 v[48:49], v13 offset0:108 offset1:109
	ds_read2st64_b32 v[50:51], v13 offset0:110 offset1:111
	ds_read_b128 v[36:39], v15 offset:416
	ds_read_b128 v[40:43], v15 offset:432
	s_waitcnt lgkmcnt(12)
	v_fmac_f32_e32 v1, v52, v60
	v_fmac_f32_e32 v1, v53, v61
	v_fmac_f32_e32 v1, v54, v62
	v_fmac_f32_e32 v1, v55, v63
	v_fmac_f32_e32 v1, v56, v64
	v_fmac_f32_e32 v1, v57, v65
	v_fmac_f32_e32 v1, v58, v66
	v_fmac_f32_e32 v1, v59, v67
	ds_read2st64_b32 v[60:61], v13 offset0:112 offset1:113
	ds_read2st64_b32 v[62:63], v13 offset0:114 offset1:115
	ds_read2st64_b32 v[64:65], v13 offset0:116 offset1:117
	ds_read2st64_b32 v[66:67], v13 offset0:118 offset1:119
	ds_read_b128 v[52:55], v15 offset:448
	ds_read_b128 v[56:59], v15 offset:464
	s_waitcnt lgkmcnt(12)
	v_fmac_f32_e32 v1, v16, v24
	v_fmac_f32_e32 v1, v17, v25
	v_fmac_f32_e32 v1, v18, v26
	v_fmac_f32_e32 v1, v19, v27
	v_fmac_f32_e32 v1, v20, v28
	v_fmac_f32_e32 v1, v21, v29
	v_fmac_f32_e32 v1, v22, v30
	v_fmac_f32_e32 v1, v23, v31
	ds_read2st64_b32 v[24:25], v13 offset0:120 offset1:121
	ds_read2st64_b32 v[26:27], v13 offset0:122 offset1:123
	ds_read2st64_b32 v[28:29], v13 offset0:124 offset1:125
	ds_read2st64_b32 v[30:31], v13 offset0:126 offset1:127
	ds_read_b128 v[16:19], v15 offset:480
	ds_read_b128 v[20:23], v15 offset:496
	s_waitcnt lgkmcnt(12)
	v_fmac_f32_e32 v1, v36, v44
	v_fmac_f32_e32 v1, v37, v45
	v_fmac_f32_e32 v1, v38, v46
	v_fmac_f32_e32 v1, v39, v47
	v_fmac_f32_e32 v1, v40, v48
	v_fmac_f32_e32 v1, v41, v49
	v_fmac_f32_e32 v1, v42, v50
	v_fmac_f32_e32 v1, v43, v51
	s_waitcnt lgkmcnt(6)
	v_fmac_f32_e32 v1, v52, v60
	v_fmac_f32_e32 v1, v53, v61
	v_fmac_f32_e32 v1, v54, v62
	v_fmac_f32_e32 v1, v55, v63
	v_fmac_f32_e32 v1, v56, v64
	v_fmac_f32_e32 v1, v57, v65
	v_fmac_f32_e32 v1, v58, v66
	v_fmac_f32_e32 v1, v59, v67
	s_waitcnt lgkmcnt(0)
	v_fmac_f32_e32 v1, v16, v24
	v_fmac_f32_e32 v1, v17, v25
	v_fmac_f32_e32 v1, v18, v26
	v_fmac_f32_e32 v1, v19, v27
	v_fmac_f32_e32 v1, v20, v28
	v_fmac_f32_e32 v1, v21, v29
	v_fmac_f32_e32 v1, v22, v30
	v_fmac_f32_e32 v1, v23, v31
	v_and_b32_e32 v13, 0x1fc, v0
	v_bfe_u32 v14, v1, 16, 1
	v_add3_u32 v1, v1, v14, s12
	v_cmp_ne_u32_e32 vcc, s14, v13
	s_nop 1
	v_cndmask_b32_sdwa v13, v3, v1, vcc dst_sel:DWORD dst_unused:UNUSED_PAD src0_sel:DWORD src1_sel:WORD_1
	v_ashrrev_i32_e32 v1, 31, v0
	v_lshlrev_b64 v[0:1], 7, v[0:1]
	v_lshl_add_u64 v[0:1], v[6:7], 0, v[0:1]
	global_store_short v[0:1], v13, off
	s_waitcnt lgkmcnt(0)
	v_mov_b32_e32 v0, v8
	s_andn2_b64 exec, exec, s[6:7]
	s_cbranch_execnz .LBB0_1199
